# final candidate but G2 epilogue f32 out stores without nt (write-back instead of streaming)
# speedup vs baseline: 1.0074x; 1.0000x over previous
; __device__ __forceinline__ unsigned cvt_pk_bf16(float lo, float hi) { f32x2_t v = {lo, hi}; bf16x2_t b = __builtin_convertvector(v, bf16x2_t); return __builtin_bit_cast(unsigned, b); }
;     __device__ __forceinline__ void operator()(const Acc& acc, const Unit& u, int wr, int wc, int fr, int fq) const {
;         const int row0 = u.pm * BM + wr * 64 + fr, col0 = u.pn * BM + wc * 32 + 8 * fq;
; #pragma unroll
;         for (int ai = 0; ai < 2; ++ai)
; #pragma unroll
;             for (int m = 0; m < 4; ++m) {
;                 const int row = row0 + ai * HALF + m * 16; float sq = 0.f;
; #pragma unroll
;                 for (int bj = 0; bj < 2; ++bj) {
;                     const size_t off = (size_t)row * DM + col0 + bj * HALF;
;                     const f32x4 b0 = *(const f32x4*)(base + off), b1 = *(const f32x4*)(base + off + 4);
;                     const f32x4 x0 = b0 + acc[ai][bj][m][0] * alpha, x1 = b1 + acc[ai][bj][m][1] * alpha;
;                     __builtin_nontemporal_store(x0, (f32x4*)(out + off)); __builtin_nontemporal_store(x1, (f32x4*)(out + off + 4));
;                     sq += (x0[0] * x0[0] + x0[1] * x0[1]) + (x0[2] * x0[2] + x0[3] * x0[3]) + (x1[0] * x1[0] + x1[1] * x1[1]) + (x1[2] * x1[2] + x1[3] * x1[3]);
;                     if (xb) { u32x4 w; w.x = cvt_pk_bf16(x0[0], x0[1]); w.y = cvt_pk_bf16(x0[2], x0[3]); w.z = cvt_pk_bf16(x1[0], x1[1]); w.w = cvt_pk_bf16(x1[2], x1[3]); *(u32x4*)(xb + off) = w; }
;                 }
;                 sq += __shfl_xor(sq, 16); sq += __shfl_xor(sq, 32);
;                 if (fq == 0) unsafeAtomicAdd(ss + row, sq);
;             }
;     }
.LBB0_299:
	s_and_b64 vcc, exec, s[46:47]
	s_cbranch_vccz .Lg2_epi_old
	v_lshl_add_u32 v146, s31, 8, v154
	v_lshl_or_b32 v144, s33, 8, v156
	v_lshl_add_u32 v145, v146, 10, v144
	v_lshlrev_b32_e32 v144, 2, v145
	v_lshlrev_b32_e32 v145, 1, v145
	v_lshlrev_b32_e32 v146, 2, v146
	v_xor_b32_e32 v147, 16, v162
	v_lshlrev_b32_e32 v147, 2, v147
	v_xor_b32_e32 v148, 32, v162
	v_lshlrev_b32_e32 v148, 2, v148
	s_mov_b64 s[72:73], s[52:53]
	global_load_dwordx4 v[180:183], v144, s[72:73]
	global_load_dwordx4 v[184:187], v144, s[72:73] offset:16
	global_load_dwordx4 v[188:191], v144, s[72:73] offset:512
	global_load_dwordx4 v[192:195], v144, s[72:73] offset:528
	s_add_u32 s72, s52, 0x10000
	s_addc_u32 s73, s53, 0
	global_load_dwordx4 v[196:199], v144, s[72:73]
	global_load_dwordx4 v[200:203], v144, s[72:73] offset:16
	global_load_dwordx4 v[204:207], v144, s[72:73] offset:512
	global_load_dwordx4 v[208:211], v144, s[72:73] offset:528
	s_waitcnt vmcnt(4)
	v_fma_f32 v124, v124, 0.5, v180
	v_fma_f32 v125, v125, 0.5, v181
	v_fma_f32 v126, v126, 0.5, v182
	v_fma_f32 v127, v127, 0.5, v183
	v_fma_f32 v120, v120, 0.5, v184
	v_fma_f32 v121, v121, 0.5, v185
	v_fma_f32 v122, v122, 0.5, v186
	v_fma_f32 v123, v123, 0.5, v187
	v_fma_f32 v116, v116, 0.5, v188
	v_fma_f32 v117, v117, 0.5, v189
	v_fma_f32 v118, v118, 0.5, v190
	v_fma_f32 v119, v119, 0.5, v191
	v_fma_f32 v112, v112, 0.5, v192
	v_fma_f32 v113, v113, 0.5, v193
	v_fma_f32 v114, v114, 0.5, v194
	v_fma_f32 v115, v115, 0.5, v195
	s_add_u32 s72, s52, 0x20000
	s_addc_u32 s73, s53, 0
	global_load_dwordx4 v[212:215], v144, s[72:73]
	global_load_dwordx4 v[216:219], v144, s[72:73] offset:16
	global_load_dwordx4 v[220:223], v144, s[72:73] offset:512
	global_load_dwordx4 v[224:227], v144, s[72:73] offset:528
	s_mov_b64 s[74:75], s[90:91]
	global_store_dwordx4 v144, v[124:127], s[74:75]
	global_store_dwordx4 v144, v[120:123], s[74:75] offset:16
	global_store_dwordx4 v144, v[116:119], s[74:75] offset:512
	global_store_dwordx4 v144, v[112:115], s[74:75] offset:528
	v_cvt_pk_bf16_f32 v232, v124, v125
	v_cvt_pk_bf16_f32 v233, v126, v127
	v_cvt_pk_bf16_f32 v234, v120, v121
	v_cvt_pk_bf16_f32 v235, v122, v123
	v_cvt_pk_bf16_f32 v236, v116, v117
	v_cvt_pk_bf16_f32 v237, v118, v119
	v_cvt_pk_bf16_f32 v238, v112, v113
	v_cvt_pk_bf16_f32 v239, v114, v115
	s_mov_b64 s[82:83], s[70:71]
	global_store_dwordx4 v145, v[232:235], s[82:83]
	global_store_dwordx4 v145, v[236:239], s[82:83] offset:256
	v_mul_f32_e32 v228, v125, v125
	v_fmac_f32_e32 v228, v124, v124
	v_mul_f32_e32 v229, v121, v121
	v_fmac_f32_e32 v229, v120, v120
	v_mul_f32_e32 v230, v117, v117
	v_fmac_f32_e32 v230, v116, v116
	v_mul_f32_e32 v231, v113, v113
	v_fmac_f32_e32 v231, v112, v112
	v_mul_f32_e32 v240, v127, v127
	v_fmac_f32_e32 v240, v126, v126
	v_mul_f32_e32 v241, v123, v123
	v_fmac_f32_e32 v241, v122, v122
	v_mul_f32_e32 v242, v119, v119
	v_fmac_f32_e32 v242, v118, v118
	v_mul_f32_e32 v243, v115, v115
	v_fmac_f32_e32 v243, v114, v114
	v_add_f32_e32 v228, v228, v240
	v_add_f32_e32 v229, v229, v241
	v_add_f32_e32 v230, v230, v242
	v_add_f32_e32 v231, v231, v243
	v_add_f32_e32 v228, v228, v229
	v_add_f32_e32 v230, v230, v231
	v_add_f32_e32 v228, v228, v230
	ds_bpermute_b32 v229, v147, v228
	s_waitcnt lgkmcnt(0)
	v_add_f32_e32 v228, v228, v229
	ds_bpermute_b32 v229, v148, v228
	s_waitcnt lgkmcnt(0)
	v_add_f32_e32 v228, v228, v229
	s_and_saveexec_b64 s[6:7], s[8:9]
	s_nop 1
	global_atomic_add_f32 v146, v228, s[44:45]
	s_mov_b64 exec, s[6:7]
	s_waitcnt vmcnt(11)
	v_fma_f32 v108, v108, 0.5, v196
	v_fma_f32 v109, v109, 0.5, v197
	v_fma_f32 v110, v110, 0.5, v198
	v_fma_f32 v111, v111, 0.5, v199
	v_fma_f32 v104, v104, 0.5, v200
	v_fma_f32 v105, v105, 0.5, v201
	v_fma_f32 v106, v106, 0.5, v202
	v_fma_f32 v107, v107, 0.5, v203
	v_fma_f32 v100, v100, 0.5, v204
	v_fma_f32 v101, v101, 0.5, v205
	v_fma_f32 v102, v102, 0.5, v206
	v_fma_f32 v103, v103, 0.5, v207
	v_fma_f32 v96, v96, 0.5, v208
	v_fma_f32 v97, v97, 0.5, v209
	v_fma_f32 v98, v98, 0.5, v210
	v_fma_f32 v99, v99, 0.5, v211
	s_add_u32 s72, s52, 0x30000
	s_addc_u32 s73, s53, 0
	global_load_dwordx4 v[180:183], v144, s[72:73]
	global_load_dwordx4 v[184:187], v144, s[72:73] offset:16
	global_load_dwordx4 v[188:191], v144, s[72:73] offset:512
	global_load_dwordx4 v[192:195], v144, s[72:73] offset:528
	s_add_u32 s74, s90, 0x10000
	s_addc_u32 s75, s91, 0
	global_store_dwordx4 v144, v[108:111], s[74:75]
	global_store_dwordx4 v144, v[104:107], s[74:75] offset:16
	global_store_dwordx4 v144, v[100:103], s[74:75] offset:512
	global_store_dwordx4 v144, v[96:99], s[74:75] offset:528
	v_cvt_pk_bf16_f32 v232, v108, v109
	v_cvt_pk_bf16_f32 v233, v110, v111
	v_cvt_pk_bf16_f32 v234, v104, v105
	v_cvt_pk_bf16_f32 v235, v106, v107
	v_cvt_pk_bf16_f32 v236, v100, v101
	v_cvt_pk_bf16_f32 v237, v102, v103
	v_cvt_pk_bf16_f32 v238, v96, v97
	v_cvt_pk_bf16_f32 v239, v98, v99
	s_add_u32 s82, s70, 0x8000
	s_addc_u32 s83, s71, 0
	global_store_dwordx4 v145, v[232:235], s[82:83]
	global_store_dwordx4 v145, v[236:239], s[82:83] offset:256
	v_mul_f32_e32 v228, v109, v109
	v_fmac_f32_e32 v228, v108, v108
	v_mul_f32_e32 v229, v105, v105
	v_fmac_f32_e32 v229, v104, v104
	v_mul_f32_e32 v230, v101, v101
	v_fmac_f32_e32 v230, v100, v100
	v_mul_f32_e32 v231, v97, v97
	v_fmac_f32_e32 v231, v96, v96
	v_mul_f32_e32 v240, v111, v111
	v_fmac_f32_e32 v240, v110, v110
	v_mul_f32_e32 v241, v107, v107
	v_fmac_f32_e32 v241, v106, v106
	v_mul_f32_e32 v242, v103, v103
	v_fmac_f32_e32 v242, v102, v102
	v_mul_f32_e32 v243, v99, v99
	v_fmac_f32_e32 v243, v98, v98
	v_add_f32_e32 v228, v228, v240
	v_add_f32_e32 v229, v229, v241
	v_add_f32_e32 v230, v230, v242
	v_add_f32_e32 v231, v231, v243
	v_add_f32_e32 v228, v228, v229
	v_add_f32_e32 v230, v230, v231
	v_add_f32_e32 v228, v228, v230
	ds_bpermute_b32 v229, v147, v228
	s_waitcnt lgkmcnt(0)
; __device__ __forceinline__ unsigned cvt_pk_bf16(float lo, float hi) { f32x2_t v = {lo, hi}; bf16x2_t b = __builtin_convertvector(v, bf16x2_t); return __builtin_bit_cast(unsigned, b); }
;     __device__ __forceinline__ void operator()(const Acc& acc, const Unit& u, int wr, int wc, int fr, int fq) const {
;         const int row0 = u.pm * BM + wr * 64 + fr, col0 = u.pn * BM + wc * 32 + 8 * fq;
; #pragma unroll
;         for (int ai = 0; ai < 2; ++ai)
; #pragma unroll
;             for (int m = 0; m < 4; ++m) {
;                 const int row = row0 + ai * HALF + m * 16; float sq = 0.f;
; #pragma unroll
;                 for (int bj = 0; bj < 2; ++bj) {
;                     const size_t off = (size_t)row * DM + col0 + bj * HALF;
;                     const f32x4 b0 = *(const f32x4*)(base + off), b1 = *(const f32x4*)(base + off + 4);
;                     const f32x4 x0 = b0 + acc[ai][bj][m][0] * alpha, x1 = b1 + acc[ai][bj][m][1] * alpha;
;                     __builtin_nontemporal_store(x0, (f32x4*)(out + off)); __builtin_nontemporal_store(x1, (f32x4*)(out + off + 4));
;                     sq += (x0[0] * x0[0] + x0[1] * x0[1]) + (x0[2] * x0[2] + x0[3] * x0[3]) + (x1[0] * x1[0] + x1[1] * x1[1]) + (x1[2] * x1[2] + x1[3] * x1[3]);
;                     if (xb) { u32x4 w; w.x = cvt_pk_bf16(x0[0], x0[1]); w.y = cvt_pk_bf16(x0[2], x0[3]); w.z = cvt_pk_bf16(x1[0], x1[1]); w.w = cvt_pk_bf16(x1[2], x1[3]); *(u32x4*)(xb + off) = w; }
;                 }
;                 sq += __shfl_xor(sq, 16); sq += __shfl_xor(sq, 32);
;                 if (fq == 0) unsafeAtomicAdd(ss + row, sq);
;             }
;     }
	v_add_f32_e32 v228, v228, v229
	ds_bpermute_b32 v229, v148, v228
	s_waitcnt lgkmcnt(0)
	v_add_f32_e32 v228, v228, v229
	s_and_saveexec_b64 s[6:7], s[8:9]
	s_nop 1
	global_atomic_add_f32 v146, v228, s[44:45] offset:64
	s_mov_b64 exec, s[6:7]
	s_waitcnt vmcnt(18)
	v_fma_f32 v92, v92, 0.5, v212
	v_fma_f32 v93, v93, 0.5, v213
	v_fma_f32 v94, v94, 0.5, v214
	v_fma_f32 v95, v95, 0.5, v215
	v_fma_f32 v88, v88, 0.5, v216
	v_fma_f32 v89, v89, 0.5, v217
	v_fma_f32 v90, v90, 0.5, v218
	v_fma_f32 v91, v91, 0.5, v219
	v_fma_f32 v84, v84, 0.5, v220
	v_fma_f32 v85, v85, 0.5, v221
	v_fma_f32 v86, v86, 0.5, v222
	v_fma_f32 v87, v87, 0.5, v223
	v_fma_f32 v80, v80, 0.5, v224
	v_fma_f32 v81, v81, 0.5, v225
	v_fma_f32 v82, v82, 0.5, v226
	v_fma_f32 v83, v83, 0.5, v227
	s_add_u32 s72, s52, 0x80000
	s_addc_u32 s73, s53, 0
	global_load_dwordx4 v[196:199], v144, s[72:73]
	global_load_dwordx4 v[200:203], v144, s[72:73] offset:16
	global_load_dwordx4 v[204:207], v144, s[72:73] offset:512
	global_load_dwordx4 v[208:211], v144, s[72:73] offset:528
	s_add_u32 s74, s90, 0x20000
	s_addc_u32 s75, s91, 0
	global_store_dwordx4 v144, v[92:95], s[74:75]
	global_store_dwordx4 v144, v[88:91], s[74:75] offset:16
	global_store_dwordx4 v144, v[84:87], s[74:75] offset:512
	global_store_dwordx4 v144, v[80:83], s[74:75] offset:528
	v_cvt_pk_bf16_f32 v232, v92, v93
	v_cvt_pk_bf16_f32 v233, v94, v95
	v_cvt_pk_bf16_f32 v234, v88, v89
	v_cvt_pk_bf16_f32 v235, v90, v91
	v_cvt_pk_bf16_f32 v236, v84, v85
	v_cvt_pk_bf16_f32 v237, v86, v87
	v_cvt_pk_bf16_f32 v238, v80, v81
	v_cvt_pk_bf16_f32 v239, v82, v83
	s_add_u32 s82, s70, 0x10000
	s_addc_u32 s83, s71, 0
	global_store_dwordx4 v145, v[232:235], s[82:83]
	global_store_dwordx4 v145, v[236:239], s[82:83] offset:256
	v_mul_f32_e32 v228, v93, v93
	v_fmac_f32_e32 v228, v92, v92
	v_mul_f32_e32 v229, v89, v89
	v_fmac_f32_e32 v229, v88, v88
	v_mul_f32_e32 v230, v85, v85
	v_fmac_f32_e32 v230, v84, v84
	v_mul_f32_e32 v231, v81, v81
	v_fmac_f32_e32 v231, v80, v80
	v_mul_f32_e32 v240, v95, v95
	v_fmac_f32_e32 v240, v94, v94
	v_mul_f32_e32 v241, v91, v91
	v_fmac_f32_e32 v241, v90, v90
	v_mul_f32_e32 v242, v87, v87
	v_fmac_f32_e32 v242, v86, v86
	v_mul_f32_e32 v243, v83, v83
	v_fmac_f32_e32 v243, v82, v82
	v_add_f32_e32 v228, v228, v240
	v_add_f32_e32 v229, v229, v241
	v_add_f32_e32 v230, v230, v242
	v_add_f32_e32 v231, v231, v243
	v_add_f32_e32 v228, v228, v229
	v_add_f32_e32 v230, v230, v231
	v_add_f32_e32 v228, v228, v230
	ds_bpermute_b32 v229, v147, v228
	s_waitcnt lgkmcnt(0)
	v_add_f32_e32 v228, v228, v229
	ds_bpermute_b32 v229, v148, v228
	s_waitcnt lgkmcnt(0)
	v_add_f32_e32 v228, v228, v229
	s_and_saveexec_b64 s[6:7], s[8:9]
	s_nop 1
	global_atomic_add_f32 v146, v228, s[44:45] offset:128
	s_mov_b64 exec, s[6:7]
	s_waitcnt vmcnt(18)
	v_fma_f32 v76, v76, 0.5, v180
	v_fma_f32 v77, v77, 0.5, v181
	v_fma_f32 v78, v78, 0.5, v182
	v_fma_f32 v79, v79, 0.5, v183
	v_fma_f32 v72, v72, 0.5, v184
	v_fma_f32 v73, v73, 0.5, v185
	v_fma_f32 v74, v74, 0.5, v186
	v_fma_f32 v75, v75, 0.5, v187
	v_fma_f32 v68, v68, 0.5, v188
	v_fma_f32 v69, v69, 0.5, v189
	v_fma_f32 v70, v70, 0.5, v190
	v_fma_f32 v71, v71, 0.5, v191
	v_fma_f32 v64, v64, 0.5, v192
	v_fma_f32 v65, v65, 0.5, v193
	v_fma_f32 v66, v66, 0.5, v194
	v_fma_f32 v67, v67, 0.5, v195
	s_add_u32 s72, s52, 0x90000
	s_addc_u32 s73, s53, 0
	global_load_dwordx4 v[212:215], v144, s[72:73]
	global_load_dwordx4 v[216:219], v144, s[72:73] offset:16
	global_load_dwordx4 v[220:223], v144, s[72:73] offset:512
	global_load_dwordx4 v[224:227], v144, s[72:73] offset:528
	s_add_u32 s74, s90, 0x30000
	s_addc_u32 s75, s91, 0
	global_store_dwordx4 v144, v[76:79], s[74:75]
	global_store_dwordx4 v144, v[72:75], s[74:75] offset:16
	global_store_dwordx4 v144, v[68:71], s[74:75] offset:512
	global_store_dwordx4 v144, v[64:67], s[74:75] offset:528
	v_cvt_pk_bf16_f32 v232, v76, v77
	v_cvt_pk_bf16_f32 v233, v78, v79
	v_cvt_pk_bf16_f32 v234, v72, v73
	v_cvt_pk_bf16_f32 v235, v74, v75
	v_cvt_pk_bf16_f32 v236, v68, v69
	v_cvt_pk_bf16_f32 v237, v70, v71
	v_cvt_pk_bf16_f32 v238, v64, v65
	v_cvt_pk_bf16_f32 v239, v66, v67
	s_add_u32 s82, s70, 0x18000
	s_addc_u32 s83, s71, 0
	global_store_dwordx4 v145, v[232:235], s[82:83]
	global_store_dwordx4 v145, v[236:239], s[82:83] offset:256
	v_mul_f32_e32 v228, v77, v77
	v_fmac_f32_e32 v228, v76, v76
	v_mul_f32_e32 v229, v73, v73
	v_fmac_f32_e32 v229, v72, v72
	v_mul_f32_e32 v230, v69, v69
	v_fmac_f32_e32 v230, v68, v68
	v_mul_f32_e32 v231, v65, v65
	v_fmac_f32_e32 v231, v64, v64
	v_mul_f32_e32 v240, v79, v79
	v_fmac_f32_e32 v240, v78, v78
	v_mul_f32_e32 v241, v75, v75
	v_fmac_f32_e32 v241, v74, v74
	v_mul_f32_e32 v242, v71, v71
	v_fmac_f32_e32 v242, v70, v70
	v_mul_f32_e32 v243, v67, v67
	v_fmac_f32_e32 v243, v66, v66
	v_add_f32_e32 v228, v228, v240
	v_add_f32_e32 v229, v229, v241
	v_add_f32_e32 v230, v230, v242
	v_add_f32_e32 v231, v231, v243
	v_add_f32_e32 v228, v228, v229
	v_add_f32_e32 v230, v230, v231
	v_add_f32_e32 v228, v228, v230
	ds_bpermute_b32 v229, v147, v228
	s_waitcnt lgkmcnt(0)
	v_add_f32_e32 v228, v228, v229
	ds_bpermute_b32 v229, v148, v228
	s_waitcnt lgkmcnt(0)
	v_add_f32_e32 v228, v228, v229
	s_and_saveexec_b64 s[6:7], s[8:9]
	s_nop 1
	global_atomic_add_f32 v146, v228, s[44:45] offset:192
	s_mov_b64 exec, s[6:7]
	s_waitcnt vmcnt(18)
; __device__ __forceinline__ unsigned cvt_pk_bf16(float lo, float hi) { f32x2_t v = {lo, hi}; bf16x2_t b = __builtin_convertvector(v, bf16x2_t); return __builtin_bit_cast(unsigned, b); }
;     __device__ __forceinline__ void operator()(const Acc& acc, const Unit& u, int wr, int wc, int fr, int fq) const {
;         const int row0 = u.pm * BM + wr * 64 + fr, col0 = u.pn * BM + wc * 32 + 8 * fq;
; #pragma unroll
;         for (int ai = 0; ai < 2; ++ai)
; #pragma unroll
;             for (int m = 0; m < 4; ++m) {
;                 const int row = row0 + ai * HALF + m * 16; float sq = 0.f;
; #pragma unroll
;                 for (int bj = 0; bj < 2; ++bj) {
;                     const size_t off = (size_t)row * DM + col0 + bj * HALF;
;                     const f32x4 b0 = *(const f32x4*)(base + off), b1 = *(const f32x4*)(base + off + 4);
;                     const f32x4 x0 = b0 + acc[ai][bj][m][0] * alpha, x1 = b1 + acc[ai][bj][m][1] * alpha;
;                     __builtin_nontemporal_store(x0, (f32x4*)(out + off)); __builtin_nontemporal_store(x1, (f32x4*)(out + off + 4));
;                     sq += (x0[0] * x0[0] + x0[1] * x0[1]) + (x0[2] * x0[2] + x0[3] * x0[3]) + (x1[0] * x1[0] + x1[1] * x1[1]) + (x1[2] * x1[2] + x1[3] * x1[3]);
;                     if (xb) { u32x4 w; w.x = cvt_pk_bf16(x0[0], x0[1]); w.y = cvt_pk_bf16(x0[2], x0[3]); w.z = cvt_pk_bf16(x1[0], x1[1]); w.w = cvt_pk_bf16(x1[2], x1[3]); *(u32x4*)(xb + off) = w; }
;                 }
;                 sq += __shfl_xor(sq, 16); sq += __shfl_xor(sq, 32);
;                 if (fq == 0) unsafeAtomicAdd(ss + row, sq);
;             }
;     }
	v_fma_f32 v60, v60, 0.5, v196
	v_fma_f32 v61, v61, 0.5, v197
	v_fma_f32 v62, v62, 0.5, v198
	v_fma_f32 v63, v63, 0.5, v199
	v_fma_f32 v56, v56, 0.5, v200
	v_fma_f32 v57, v57, 0.5, v201
	v_fma_f32 v58, v58, 0.5, v202
	v_fma_f32 v59, v59, 0.5, v203
	v_fma_f32 v52, v52, 0.5, v204
	v_fma_f32 v53, v53, 0.5, v205
	v_fma_f32 v54, v54, 0.5, v206
	v_fma_f32 v55, v55, 0.5, v207
	v_fma_f32 v48, v48, 0.5, v208
	v_fma_f32 v49, v49, 0.5, v209
	v_fma_f32 v50, v50, 0.5, v210
	v_fma_f32 v51, v51, 0.5, v211
	s_add_u32 s72, s52, 0xa0000
	s_addc_u32 s73, s53, 0
	global_load_dwordx4 v[180:183], v144, s[72:73]
	global_load_dwordx4 v[184:187], v144, s[72:73] offset:16
	global_load_dwordx4 v[188:191], v144, s[72:73] offset:512
	global_load_dwordx4 v[192:195], v144, s[72:73] offset:528
	s_add_u32 s74, s90, 0x80000
	s_addc_u32 s75, s91, 0
	global_store_dwordx4 v144, v[60:63], s[74:75]
	global_store_dwordx4 v144, v[56:59], s[74:75] offset:16
	global_store_dwordx4 v144, v[52:55], s[74:75] offset:512
	global_store_dwordx4 v144, v[48:51], s[74:75] offset:528
	v_cvt_pk_bf16_f32 v232, v60, v61
	v_cvt_pk_bf16_f32 v233, v62, v63
	v_cvt_pk_bf16_f32 v234, v56, v57
	v_cvt_pk_bf16_f32 v235, v58, v59
	v_cvt_pk_bf16_f32 v236, v52, v53
	v_cvt_pk_bf16_f32 v237, v54, v55
	v_cvt_pk_bf16_f32 v238, v48, v49
	v_cvt_pk_bf16_f32 v239, v50, v51
	s_add_u32 s82, s70, 0x40000
	s_addc_u32 s83, s71, 0
	global_store_dwordx4 v145, v[232:235], s[82:83]
	global_store_dwordx4 v145, v[236:239], s[82:83] offset:256
	v_mul_f32_e32 v228, v61, v61
	v_fmac_f32_e32 v228, v60, v60
	v_mul_f32_e32 v229, v57, v57
	v_fmac_f32_e32 v229, v56, v56
	v_mul_f32_e32 v230, v53, v53
	v_fmac_f32_e32 v230, v52, v52
	v_mul_f32_e32 v231, v49, v49
	v_fmac_f32_e32 v231, v48, v48
	v_mul_f32_e32 v240, v63, v63
	v_fmac_f32_e32 v240, v62, v62
	v_mul_f32_e32 v241, v59, v59
	v_fmac_f32_e32 v241, v58, v58
	v_mul_f32_e32 v242, v55, v55
	v_fmac_f32_e32 v242, v54, v54
	v_mul_f32_e32 v243, v51, v51
	v_fmac_f32_e32 v243, v50, v50
	v_add_f32_e32 v228, v228, v240
	v_add_f32_e32 v229, v229, v241
	v_add_f32_e32 v230, v230, v242
	v_add_f32_e32 v231, v231, v243
	v_add_f32_e32 v228, v228, v229
	v_add_f32_e32 v230, v230, v231
	v_add_f32_e32 v228, v228, v230
	ds_bpermute_b32 v229, v147, v228
	s_waitcnt lgkmcnt(0)
	v_add_f32_e32 v228, v228, v229
	ds_bpermute_b32 v229, v148, v228
	s_waitcnt lgkmcnt(0)
	v_add_f32_e32 v228, v228, v229
	s_and_saveexec_b64 s[6:7], s[8:9]
	s_nop 1
	global_atomic_add_f32 v146, v228, s[44:45] offset:512
	s_mov_b64 exec, s[6:7]
	s_waitcnt vmcnt(18)
	v_fma_f32 v44, v44, 0.5, v212
	v_fma_f32 v45, v45, 0.5, v213
	v_fma_f32 v46, v46, 0.5, v214
	v_fma_f32 v47, v47, 0.5, v215
	v_fma_f32 v40, v40, 0.5, v216
	v_fma_f32 v41, v41, 0.5, v217
	v_fma_f32 v42, v42, 0.5, v218
	v_fma_f32 v43, v43, 0.5, v219
	v_fma_f32 v36, v36, 0.5, v220
	v_fma_f32 v37, v37, 0.5, v221
	v_fma_f32 v38, v38, 0.5, v222
	v_fma_f32 v39, v39, 0.5, v223
	v_fma_f32 v32, v32, 0.5, v224
	v_fma_f32 v33, v33, 0.5, v225
	v_fma_f32 v34, v34, 0.5, v226
	v_fma_f32 v35, v35, 0.5, v227
	s_add_u32 s72, s52, 0xb0000
	s_addc_u32 s73, s53, 0
	global_load_dwordx4 v[196:199], v144, s[72:73]
	global_load_dwordx4 v[200:203], v144, s[72:73] offset:16
	global_load_dwordx4 v[204:207], v144, s[72:73] offset:512
	global_load_dwordx4 v[208:211], v144, s[72:73] offset:528
	s_add_u32 s74, s90, 0x90000
	s_addc_u32 s75, s91, 0
	global_store_dwordx4 v144, v[44:47], s[74:75]
	global_store_dwordx4 v144, v[40:43], s[74:75] offset:16
	global_store_dwordx4 v144, v[36:39], s[74:75] offset:512
	global_store_dwordx4 v144, v[32:35], s[74:75] offset:528
	v_cvt_pk_bf16_f32 v232, v44, v45
	v_cvt_pk_bf16_f32 v233, v46, v47
	v_cvt_pk_bf16_f32 v234, v40, v41
	v_cvt_pk_bf16_f32 v235, v42, v43
	v_cvt_pk_bf16_f32 v236, v36, v37
	v_cvt_pk_bf16_f32 v237, v38, v39
	v_cvt_pk_bf16_f32 v238, v32, v33
	v_cvt_pk_bf16_f32 v239, v34, v35
	s_add_u32 s82, s70, 0x48000
	s_addc_u32 s83, s71, 0
	global_store_dwordx4 v145, v[232:235], s[82:83]
	global_store_dwordx4 v145, v[236:239], s[82:83] offset:256
	v_mul_f32_e32 v228, v45, v45
	v_fmac_f32_e32 v228, v44, v44
	v_mul_f32_e32 v229, v41, v41
	v_fmac_f32_e32 v229, v40, v40
	v_mul_f32_e32 v230, v37, v37
	v_fmac_f32_e32 v230, v36, v36
	v_mul_f32_e32 v231, v33, v33
	v_fmac_f32_e32 v231, v32, v32
	v_mul_f32_e32 v240, v47, v47
	v_fmac_f32_e32 v240, v46, v46
	v_mul_f32_e32 v241, v43, v43
	v_fmac_f32_e32 v241, v42, v42
	v_mul_f32_e32 v242, v39, v39
	v_fmac_f32_e32 v242, v38, v38
	v_mul_f32_e32 v243, v35, v35
	v_fmac_f32_e32 v243, v34, v34
	v_add_f32_e32 v228, v228, v240
	v_add_f32_e32 v229, v229, v241
	v_add_f32_e32 v230, v230, v242
	v_add_f32_e32 v231, v231, v243
	v_add_f32_e32 v228, v228, v229
	v_add_f32_e32 v230, v230, v231
	v_add_f32_e32 v228, v228, v230
	ds_bpermute_b32 v229, v147, v228
	s_waitcnt lgkmcnt(0)
; __device__ __forceinline__ unsigned cvt_pk_bf16(float lo, float hi) { f32x2_t v = {lo, hi}; bf16x2_t b = __builtin_convertvector(v, bf16x2_t); return __builtin_bit_cast(unsigned, b); }
;     __device__ __forceinline__ void operator()(const Acc& acc, const Unit& u, int wr, int wc, int fr, int fq) const {
;         const int row0 = u.pm * BM + wr * 64 + fr, col0 = u.pn * BM + wc * 32 + 8 * fq;
; #pragma unroll
;         for (int ai = 0; ai < 2; ++ai)
; #pragma unroll
;             for (int m = 0; m < 4; ++m) {
;                 const int row = row0 + ai * HALF + m * 16; float sq = 0.f;
; #pragma unroll
;                 for (int bj = 0; bj < 2; ++bj) {
;                     const size_t off = (size_t)row * DM + col0 + bj * HALF;
;                     const f32x4 b0 = *(const f32x4*)(base + off), b1 = *(const f32x4*)(base + off + 4);
;                     const f32x4 x0 = b0 + acc[ai][bj][m][0] * alpha, x1 = b1 + acc[ai][bj][m][1] * alpha;
;                     __builtin_nontemporal_store(x0, (f32x4*)(out + off)); __builtin_nontemporal_store(x1, (f32x4*)(out + off + 4));
;                     sq += (x0[0] * x0[0] + x0[1] * x0[1]) + (x0[2] * x0[2] + x0[3] * x0[3]) + (x1[0] * x1[0] + x1[1] * x1[1]) + (x1[2] * x1[2] + x1[3] * x1[3]);
;                     if (xb) { u32x4 w; w.x = cvt_pk_bf16(x0[0], x0[1]); w.y = cvt_pk_bf16(x0[2], x0[3]); w.z = cvt_pk_bf16(x1[0], x1[1]); w.w = cvt_pk_bf16(x1[2], x1[3]); *(u32x4*)(xb + off) = w; }
;                 }
;                 sq += __shfl_xor(sq, 16); sq += __shfl_xor(sq, 32);
;                 if (fq == 0) unsafeAtomicAdd(ss + row, sq);
;             }
;     }
	v_add_f32_e32 v228, v228, v229
	ds_bpermute_b32 v229, v148, v228
	s_waitcnt lgkmcnt(0)
	v_add_f32_e32 v228, v228, v229
	s_and_saveexec_b64 s[6:7], s[8:9]
	s_nop 1
	global_atomic_add_f32 v146, v228, s[44:45] offset:576
	s_mov_b64 exec, s[6:7]
	s_waitcnt vmcnt(18)
	v_fma_f32 v28, v28, 0.5, v180
	v_fma_f32 v29, v29, 0.5, v181
	v_fma_f32 v30, v30, 0.5, v182
	v_fma_f32 v31, v31, 0.5, v183
	v_fma_f32 v24, v24, 0.5, v184
	v_fma_f32 v25, v25, 0.5, v185
	v_fma_f32 v26, v26, 0.5, v186
	v_fma_f32 v27, v27, 0.5, v187
	v_fma_f32 v20, v20, 0.5, v188
	v_fma_f32 v21, v21, 0.5, v189
	v_fma_f32 v22, v22, 0.5, v190
	v_fma_f32 v23, v23, 0.5, v191
	v_fma_f32 v16, v16, 0.5, v192
	v_fma_f32 v17, v17, 0.5, v193
	v_fma_f32 v18, v18, 0.5, v194
	v_fma_f32 v19, v19, 0.5, v195
	s_add_u32 s74, s90, 0xa0000
	s_addc_u32 s75, s91, 0
	global_store_dwordx4 v144, v[28:31], s[74:75]
	global_store_dwordx4 v144, v[24:27], s[74:75] offset:16
	global_store_dwordx4 v144, v[20:23], s[74:75] offset:512
	global_store_dwordx4 v144, v[16:19], s[74:75] offset:528
	v_cvt_pk_bf16_f32 v232, v28, v29
	v_cvt_pk_bf16_f32 v233, v30, v31
	v_cvt_pk_bf16_f32 v234, v24, v25
	v_cvt_pk_bf16_f32 v235, v26, v27
	v_cvt_pk_bf16_f32 v236, v20, v21
	v_cvt_pk_bf16_f32 v237, v22, v23
	v_cvt_pk_bf16_f32 v238, v16, v17
	v_cvt_pk_bf16_f32 v239, v18, v19
	s_add_u32 s82, s70, 0x50000
	s_addc_u32 s83, s71, 0
	global_store_dwordx4 v145, v[232:235], s[82:83]
	global_store_dwordx4 v145, v[236:239], s[82:83] offset:256
	v_mul_f32_e32 v228, v29, v29
	v_fmac_f32_e32 v228, v28, v28
	v_mul_f32_e32 v229, v25, v25
	v_fmac_f32_e32 v229, v24, v24
	v_mul_f32_e32 v230, v21, v21
	v_fmac_f32_e32 v230, v20, v20
	v_mul_f32_e32 v231, v17, v17
	v_fmac_f32_e32 v231, v16, v16
	v_mul_f32_e32 v240, v31, v31
	v_fmac_f32_e32 v240, v30, v30
	v_mul_f32_e32 v241, v27, v27
	v_fmac_f32_e32 v241, v26, v26
	v_mul_f32_e32 v242, v23, v23
	v_fmac_f32_e32 v242, v22, v22
	v_mul_f32_e32 v243, v19, v19
	v_fmac_f32_e32 v243, v18, v18
	v_add_f32_e32 v228, v228, v240
	v_add_f32_e32 v229, v229, v241
	v_add_f32_e32 v230, v230, v242
	v_add_f32_e32 v231, v231, v243
	v_add_f32_e32 v228, v228, v229
	v_add_f32_e32 v230, v230, v231
	v_add_f32_e32 v228, v228, v230
	ds_bpermute_b32 v229, v147, v228
	s_waitcnt lgkmcnt(0)
	v_add_f32_e32 v228, v228, v229
	ds_bpermute_b32 v229, v148, v228
	s_waitcnt lgkmcnt(0)
	v_add_f32_e32 v228, v228, v229
	s_and_saveexec_b64 s[6:7], s[8:9]
	s_nop 1
	global_atomic_add_f32 v146, v228, s[44:45] offset:640
	s_mov_b64 exec, s[6:7]
	s_waitcnt vmcnt(14)
	v_fma_f32 v12, v12, 0.5, v196
	v_fma_f32 v13, v13, 0.5, v197
	v_fma_f32 v14, v14, 0.5, v198
	v_fma_f32 v15, v15, 0.5, v199
	v_fma_f32 v8, v8, 0.5, v200
	v_fma_f32 v9, v9, 0.5, v201
	v_fma_f32 v10, v10, 0.5, v202
	v_fma_f32 v11, v11, 0.5, v203
	v_fma_f32 v4, v4, 0.5, v204
	v_fma_f32 v5, v5, 0.5, v205
	v_fma_f32 v6, v6, 0.5, v206
	v_fma_f32 v7, v7, 0.5, v207
	v_fma_f32 v0, v0, 0.5, v208
	v_fma_f32 v1, v1, 0.5, v209
	v_fma_f32 v2, v2, 0.5, v210
	v_fma_f32 v3, v3, 0.5, v211
	s_add_u32 s74, s90, 0xb0000
	s_addc_u32 s75, s91, 0
	global_store_dwordx4 v144, v[12:15], s[74:75]
	global_store_dwordx4 v144, v[8:11], s[74:75] offset:16
	global_store_dwordx4 v144, v[4:7], s[74:75] offset:512
	global_store_dwordx4 v144, v[0:3], s[74:75] offset:528
	v_cvt_pk_bf16_f32 v232, v12, v13
	v_cvt_pk_bf16_f32 v233, v14, v15
	v_cvt_pk_bf16_f32 v234, v8, v9
	v_cvt_pk_bf16_f32 v235, v10, v11
	v_cvt_pk_bf16_f32 v236, v4, v5
	v_cvt_pk_bf16_f32 v237, v6, v7
	v_cvt_pk_bf16_f32 v238, v0, v1
	v_cvt_pk_bf16_f32 v239, v2, v3
	s_add_u32 s82, s70, 0x58000
	s_addc_u32 s83, s71, 0
	global_store_dwordx4 v145, v[232:235], s[82:83]
	global_store_dwordx4 v145, v[236:239], s[82:83] offset:256
	v_mul_f32_e32 v228, v13, v13
	v_fmac_f32_e32 v228, v12, v12
	v_mul_f32_e32 v229, v9, v9
	v_fmac_f32_e32 v229, v8, v8
	v_mul_f32_e32 v230, v5, v5
	v_fmac_f32_e32 v230, v4, v4
	v_mul_f32_e32 v231, v1, v1
	v_fmac_f32_e32 v231, v0, v0
	v_mul_f32_e32 v240, v15, v15
	v_fmac_f32_e32 v240, v14, v14
	v_mul_f32_e32 v241, v11, v11
	v_fmac_f32_e32 v241, v10, v10
	v_mul_f32_e32 v242, v7, v7
	v_fmac_f32_e32 v242, v6, v6
	v_mul_f32_e32 v243, v3, v3
	v_fmac_f32_e32 v243, v2, v2
	v_add_f32_e32 v228, v228, v240
	v_add_f32_e32 v229, v229, v241
	v_add_f32_e32 v230, v230, v242
	v_add_f32_e32 v231, v231, v243
	v_add_f32_e32 v228, v228, v229
	v_add_f32_e32 v230, v230, v231
	v_add_f32_e32 v228, v228, v230
	ds_bpermute_b32 v229, v147, v228
	s_waitcnt lgkmcnt(0)
	v_add_f32_e32 v228, v228, v229
	ds_bpermute_b32 v229, v148, v228
	s_waitcnt lgkmcnt(0)
	v_add_f32_e32 v228, v228, v229
	s_and_saveexec_b64 s[6:7], s[8:9]
	s_nop 1
	global_atomic_add_f32 v146, v228, s[44:45] offset:704
	s_mov_b64 exec, s[6:7]
	s_branch .Lg2_epi_done
